# s10 + p1_stagger8: the 112 five-tile workgroups start P1 8 us late so tile-epilogue store bursts of the two groups interleave
# baseline (speedup 1.0000x reference)
.LBB0_103:
	s_cmp_lt_i32 s82, 2
	s_cselect_b64 s[4:5], -1, 0
	s_add_u32 s6, s80, 0x1100000
	v_writelane_b32 v255, s84, 25
	s_addc_u32 s7, s81, 0
	v_writelane_b32 v255, s6, 26
	s_nop 1
	v_writelane_b32 v255, s7, 27
	s_add_u32 s6, s80, 0x1300000
	s_addc_u32 s7, s81, 0
	v_writelane_b32 v255, s6, 28
	s_nop 1
	v_writelane_b32 v255, s7, 29
	s_add_u32 s6, s80, 0x1b00000
	s_addc_u32 s7, s81, 0
	s_add_u32 s69, s80, 0x2600000
	v_writelane_b32 v255, s6, 30
	s_addc_u32 s70, s81, 0
	s_nop 0
	v_writelane_b32 v255, s7, 31
	s_add_u32 s6, s80, 0x2c00000
	s_addc_u32 s7, s81, 0
	s_add_u32 s60, s80, 0x8c00000
	s_addc_u32 s61, s81, 0
	s_add_u32 s96, s80, 0xdc00000
	s_addc_u32 s91, s81, 0
	s_add_u32 s62, s80, 0x7c00000
	v_writelane_b32 v255, s6, 32
	s_addc_u32 s63, s81, 0
	s_and_b64 s[28:29], s[4:5], s[0:1]
	v_writelane_b32 v255, s7, 33
	s_andn2_b64 vcc, exec, s[28:29]
	s_cbranch_vccnz .LBB0_220
	s_cmp_lt_u32 s2, 0x90
	s_cbranch_scc1 .Lp1_nodelay
	s_cmp_lg_u32 s3, 0x100
	s_cbranch_scc1 .Lp1_nodelay
	s_memrealtime s[98:99]
	s_waitcnt lgkmcnt(0)
	s_add_u32 s98, s98, 0x320
.Lp1_dl:
	s_sleep 8
	s_memrealtime s[100:101]
	s_waitcnt lgkmcnt(0)
	s_sub_u32 s100, s100, s98
	s_cmp_lt_i32 s100, 0
	s_cbranch_scc1 .Lp1_dl
.Lp1_nodelay:
	s_cmpk_lt_i32 s2, 0x590
	s_cselect_b64 s[4:5], -1, 0
	s_cmpk_gt_i32 s2, 0x58f
	v_readfirstlane_b32 s6, v216
	s_cbranch_scc1 .LBB0_107
	s_cmpk_gt_i32 s2, 0x57f
	s_cbranch_scc1 .LBB0_108
	s_ashr_i32 s0, s2, 31
	s_lshr_b32 s0, s0, 29
	s_add_i32 s0, s2, s0
	s_ashr_i32 s1, s0, 3
	s_and_b32 s0, s0, -8
	s_sub_i32 s0, s2, s0
	s_cmp_lt_i32 s0, 0
	s_movk_i32 s7, 0xb1
	s_cselect_b32 s7, s7, 0xb0
	s_mul_i32 s0, s0, s7
	s_add_i32 s0, s0, s1
	s_mul_hi_i32 s1, s0, 0x2e8ba2e9
	s_lshr_b32 s7, s1, 31
	s_ashr_i32 s1, s1, 5
	s_add_i32 s1, s1, s7
	s_lshl_b32 s7, s1, 3
	s_mulk_i32 s1, 0xb0
	s_sub_i32 s0, s0, s1
	s_sext_i32_i16 s1, s0
	s_bfe_u32 s1, s1, 0x3001c
	s_add_i32 s1, s0, s1
	s_bfe_u32 s8, s1, 0xd0003
	s_and_b32 s1, s1, 0xfff8
	s_sub_i32 s0, s0, s1
	s_sext_i32_i16 s0, s0
	s_add_i32 s8, s8, 0
	s_add_i32 s38, s7, s0
	s_bfe_i32 s0, s8, 0x80000
	s_mul_i32 s0, s0, 0xffbb
	s_bfe_u32 s0, s0, 0x80008
	s_add_i32 s0, s0, s8
	s_bfe_i32 s1, s0, 0x80000
	s_and_b32 s1, 0xffff, s1
	s_lshr_b32 s1, s1, 4
	s_bfe_u32 s0, s0, 0x10007
	s_add_i32 s0, s1, s0
	s_mul_i32 s0, s0, 22
	s_sub_i32 s0, s8, s0
	s_mov_b32 s59, 0
	s_sext_i32_i8 s90, s0
	s_mov_b64 s[0:1], -1
	s_andn2_b64 vcc, exec, s[4:5]
	v_lshlrev_b32_e32 v16, 2, v216
	s_cbranch_vccz .LBB0_109
	s_branch .LBB0_178
